# same as previous plus a longer wait-state pad (s_nop 7) between v_readlane of the gla_norm pointer and the first load through it in phase 6 part 1
# baseline (speedup 1.0000x reference)
; DI float bflo(unsigned u) { return __uint_as_float(u << 16); }
; DI float bfhi(unsigned u) { return __uint_as_float(u & 0xffff0000u); }
; DI void phase_mergeprep(const P& p, int bid, int nb) {
;     ...
;     for (int row = bid * 8 + wid; row < T; row += nb * 8) {
;       const int c0 = lane * 16; const bf16_t* op = O + (size_t)row * 1024 + c0;
;       f32x4 v[4]; float ss = 0.f;
;       const bf16_t* ofp = (const bf16_t*)(p.ws + OFF_OFB) + (size_t)row * 1024 + c0; const bf16_t* obp = ofp + (size_t)T * 1024;
;       u32x4 f0 = *(const u32x4*)ofp, f1 = *(const u32x4*)(ofp + 8), b0 = *(const u32x4*)obp, b1 = *(const u32x4*)(obp + 8);
;       const u32x4 i0 = *(const u32x4*)op, i1 = *(const u32x4*)(op + 8);
; #pragma unroll
;       for (int q = 0; q < 4; ++q) { const unsigned ia = q < 2 ? i0[2 * (q & 1)] : i1[2 * (q & 1)], ib = q < 2 ? i0[2 * (q & 1) + 1] : i1[2 * (q & 1) + 1];
;         v[q] = (f32x4){bflo(ia), bfhi(ia), bflo(ib), bfhi(ib)};
;         const unsigned fa = q < 2 ? f0[2 * (q & 1)] : f1[2 * (q & 1)], fb = q < 2 ? f0[2 * (q & 1) + 1] : f1[2 * (q & 1) + 1];
;         const unsigned ba = q < 2 ? b0[2 * (q & 1)] : b1[2 * (q & 1)], bb = q < 2 ? b0[2 * (q & 1) + 1] : b1[2 * (q & 1) + 1];
;         v[q].x += bflo(fa) + bflo(ba); v[q].y += bfhi(fa) + bfhi(ba); v[q].z += bflo(fb) + bflo(bb); v[q].w += bfhi(fb) + bfhi(bb);
;         ss += v[q].x * v[q].x + v[q].y * v[q].y + v[q].z * v[q].z + v[q].w * v[q].w; }
;       ss += __shfl_xor(ss, 1, 64); ss += __shfl_xor(ss, 2, 64); ss += __shfl_xor(ss, 4, 64); ss += __shfl_xor(ss, 8, 64);
;       const float rstd = rsqrtf(ss * (1.f / 256.f) + 1e-6f);
;       const bf16_t* gp = G + (size_t)row * 1024 + c0; u32x4 g0 = *(const u32x4*)gp, g1 = *(const u32x4*)(gp + 8);
;       const float* nw = p.gla_norm + (c0 & 255);
.LBB0_508:
	s_waitcnt vmcnt(0)
	v_lshrrev_b32_e32 v4, 6, v29
	s_lshl_b32 s0, s2, 3
	v_add_u32_e32 v5, s0, v4
	v_and_b32_e32 v3, 63, v29
	v_lshlrev_b32_e32 v2, 5, v3
	v_readfirstlane_b32 s3, v5
	v_and_b32_e32 v6, 15, v3
	v_lshlrev_b32_e32 v6, 6, v6
	v_xor_b32_e32 v8, 1, v3
	v_lshlrev_b32_e32 v8, 2, v8
	v_xor_b32_e32 v9, 2, v3
	v_lshlrev_b32_e32 v9, 2, v9
	v_xor_b32_e32 v10, 4, v3
	v_lshlrev_b32_e32 v10, 2, v10
	v_xor_b32_e32 v11, 8, v3
	v_lshlrev_b32_e32 v11, 2, v11
	s_lshl_b32 s6, s88, 3
	s_mov_b32 s7, 0x8000
	s_cmp_ge_i32 s3, s7
	s_cbranch_scc1 .Lma_done
	v_readlane_b32 s26, v254, 30
	v_readlane_b32 s27, v254, 31
	s_nop 7
	global_load_dwordx4 v[16:19], v6, s[26:27]
	global_load_dwordx4 v[20:23], v6, s[26:27] offset:16
	global_load_dwordx4 v[24:27], v6, s[26:27] offset:32
	global_load_dwordx4 v[28:31], v6, s[26:27] offset:48
	s_lshl_b32 s10, s3, 11
	s_add_u32 s12, s84, s10
	s_addc_u32 s13, s85, 0
	s_add_u32 s14, s12, 0x2bd00000
	s_addc_u32 s15, s13, 0
	s_add_u32 s16, s12, 0xbb00000
	s_addc_u32 s17, s13, 0
	s_add_u32 s18, s12, 0xfb00000
	s_addc_u32 s19, s13, 0
	s_add_u32 s20, s12, 0x1bd00000
	s_addc_u32 s21, s13, 0
	global_load_dwordx4 v[32:35], v2, s[14:15]
	global_load_dwordx4 v[36:39], v2, s[14:15] offset:16
	global_load_dwordx4 v[40:43], v2, s[16:17]
	global_load_dwordx4 v[44:47], v2, s[16:17] offset:16
	global_load_dwordx4 v[48:51], v2, s[18:19]
	global_load_dwordx4 v[52:55], v2, s[18:19] offset:16
	global_load_dwordx4 v[56:59], v2, s[20:21]
	global_load_dwordx4 v[60:63], v2, s[20:21] offset:16
